# topgen kernel plus stagger-barrier sinking in the FFN in-projection: the trailing half's re-stagger barrier is executed after the next-unit tile decode (start of the peeled iteration) instead of at th
# baseline (speedup 1.0000x reference)
; #define PG8_STAGE(bufoff, gbase, voff) do { _Pragma("unroll") for (int _i = 0; _i < 2; ++_i) \
;         __builtin_amdgcn_global_load_lds((const unsigned*)((const char*)(gbase) + (voff)[_i]), (PG8_LAS unsigned*)(lds + (bufoff) + ldsw + _i * 8192), 16, 0, 0); } while (0)
; #define PG8_LDA(dst, b, h) do { _Pragma("unroll") for (int m = 0; m < 4; ++m) _Pragma("unroll") for (int k = 0; k < 2; ++k) dst[m][k] = *(const PG8_LAS bf16x8*)(lds + PG8_SA(b, h) + aoff + m * 2048 + k * 1024); } while (0)
; #define PG8_LDB(dst, b, h) do { _Pragma("unroll") for (int n = 0; n < 2; ++n) _Pragma("unroll") for (int k = 0; k < 2; ++k) dst[n][k] = *(const PG8_LAS bf16x8*)(lds + PG8_SB(b, h) + boff + n * 2048 + k * 1024); } while (0)
; #define PG8_BAR __builtin_amdgcn_s_barrier()
; #define PG8_SCHED __builtin_amdgcn_sched_barrier(0)
; template <class Epi, class Sched, bool ALIGN_EPI = false, bool SP2 = false>
; __device__ __forceinline__ void gemm_phase(PG8_LAS unsigned char* lds, const Gemm g, const Sched& S, const Epi& E) {
;     ...
;             PG8_LDB(B0, 0, 0); PG8_LDB(B1, 0, 1); PG8_SCHED; PG8_LDA(At, 0, 0); PG8_STAGE(PG8_SA(1, 1), a1 + hstep, voffA);
;     ...
;         if constexpr (ALIGN_EPI) { if (wr == 1) PG8_BAR; }
.Lpeel_go_0:
	s_andn2_b64 vcc, exec, s[10:11]
	s_cbranch_vccnz .Lpeel_nostag_0
	s_barrier

;     __device__ __forceinline__ void operator()(const f32x4 (&acc)[2][2][4][2], const Unit& u, int wr, int wc, int fr, int fq) const {
;         asm volatile("" : "+v"(fr), "+v"(fq));
;         const int row0 = u.pm * BM + wr * 64 + fr, col0 = u.pn * 128 + wc * 32 + 8 * fq;
;         rt.refresh(ssp, u.pm, wr, fr, fq);
; #pragma unroll
;         for (int ai = 0; ai < 2; ++ai)
; #pragma unroll
;             for (int m = 0; m < 4; ++m) {
;                 const int row = row0 + ai * HALF + m * 16;
;                 const float rs = rt.get(ai, m, fr), rsl = rs * -LOG2E_F, irs2 = __builtin_amdgcn_rcpf(rs * rs);
;                 float o[8];
; #pragma unroll
;                 for (int n = 0; n < 2; ++n) {
;                     const f32x4 a = acc[ai][0][m][n], b = acc[ai][1][m][n];
;                     const f32x4 t = a * rsl, ab = a * b;
;                     f32x4 e; e[0] = __builtin_amdgcn_exp2f(t[0]); e[1] = __builtin_amdgcn_exp2f(t[1]); e[2] = __builtin_amdgcn_exp2f(t[2]); e[3] = __builtin_amdgcn_exp2f(t[3]);
;                     const f32x4 d = e * irs2 + irs2;
;                     f32x4 r; r[0] = __builtin_amdgcn_rcpf(d[0]); r[1] = __builtin_amdgcn_rcpf(d[1]); r[2] = __builtin_amdgcn_rcpf(d[2]); r[3] = __builtin_amdgcn_rcpf(d[3]);
;                     const f32x4 q = ab * r;
;                     o[n * 4 + 0] = q[0]; o[n * 4 + 1] = q[1]; o[n * 4 + 2] = q[2]; o[n * 4 + 3] = q[3];
;                 }
;                 { const u32x4 pk_ = pack8(o); *(u32x4*)(O + (size_t)row * ldo + col0) = pk_;
.LBB0_115:
	v_lshl_add_u32 v146, v145, 2, s3
	ds_read2_b32 v[148:149], v146 offset1:16
	s_lshl_b32 s17, s60, 7
	s_or_b32 s17, s17, s55
	v_lshl_add_u32 v150, v147, 3, s17
	v_pk_mul_f32 v[124:125], v[128:129], v[124:125]
	s_waitcnt lgkmcnt(0)
	v_mul_f32_e32 v152, 0xbfb8aa3b, v148
	v_mul_f32_e32 v147, v148, v148
	v_pk_mul_f32 v[154:155], v[128:129], v[152:153] op_sel_hi:[1,0]
	v_pk_mul_f32 v[156:157], v[126:127], v[152:153] op_sel_hi:[1,0]
	v_rcp_f32_e32 v148, v147
	v_exp_f32_e32 v156, v156
	v_exp_f32_e32 v154, v154
	v_exp_f32_e32 v155, v155
	v_exp_f32_e32 v157, v157
	v_pk_mul_f32 v[122:123], v[126:127], v[122:123]
	v_pk_mul_f32 v[114:115], v[118:119], v[114:115]
	v_pk_fma_f32 v[126:127], v[148:149], v[154:155], v[148:149] op_sel_hi:[0,1,0]
	v_pk_fma_f32 v[128:129], v[148:149], v[156:157], v[148:149] op_sel_hi:[0,1,0]
	v_pk_mul_f32 v[154:155], v[120:121], v[152:153] op_sel_hi:[1,0]
	v_pk_mul_f32 v[152:153], v[118:119], v[152:153] op_sel_hi:[1,0]
	v_rcp_f32_e32 v128, v128
	v_rcp_f32_e32 v129, v129
	v_exp_f32_e32 v152, v152
	v_exp_f32_e32 v153, v153
	v_rcp_f32_e32 v126, v126
	v_rcp_f32_e32 v127, v127
	v_exp_f32_e32 v154, v154
	v_exp_f32_e32 v155, v155
	v_pk_mul_f32 v[122:123], v[122:123], v[128:129]
	v_pk_fma_f32 v[128:129], v[148:149], v[152:153], v[148:149] op_sel_hi:[0,1,0]
	v_pk_mul_f32 v[124:125], v[124:125], v[126:127]
	v_pk_fma_f32 v[126:127], v[148:149], v[154:155], v[148:149] op_sel_hi:[0,1,0]
	v_rcp_f32_e32 v128, v128
	v_rcp_f32_e32 v129, v129
	v_rcp_f32_e32 v126, v126
	v_rcp_f32_e32 v127, v127
	v_pk_mul_f32 v[116:117], v[120:121], v[116:117]
	v_pk_mul_f32 v[114:115], v[114:115], v[128:129]
	v_add_u32_e32 v145, s15, v145
	v_ashrrev_i32_e32 v151, 31, v150
	v_pk_mul_f32 v[116:117], v[116:117], v[126:127]
	v_cvt_pk_bf16_f32 v120, v114, v115
	v_mov_b64_e32 v[114:115], s[24:25]
	v_cvt_pk_bf16_f32 v118, v122, v123
	v_cvt_pk_bf16_f32 v121, v116, v117
	v_mad_i64_i32 v[122:123], s[44:45], v145, s29, v[114:115]
	v_lshlrev_b64 v[116:117], 1, v[150:151]
	v_cvt_pk_bf16_f32 v119, v124, v125
	v_lshl_add_u64 v[122:123], v[122:123], 0, v[116:117]
	global_store_dwordx4 v[122:123], v[118:121], off
	v_pk_mul_f32 v[108:109], v[112:113], v[108:109]
	v_pk_mul_f32 v[106:107], v[110:111], v[106:107]
	v_mul_f32_e32 v118, 0xbfb8aa3b, v149
	v_mul_f32_e32 v119, v149, v149
	v_pk_mul_f32 v[122:123], v[112:113], v[118:119] op_sel_hi:[1,0]
	v_pk_mul_f32 v[124:125], v[110:111], v[118:119] op_sel_hi:[1,0]
	v_rcp_f32_e32 v120, v119
	v_exp_f32_e32 v124, v124
	v_exp_f32_e32 v122, v122
	v_exp_f32_e32 v123, v123
	v_exp_f32_e32 v125, v125
	v_pk_mul_f32 v[100:101], v[104:105], v[100:101]
	v_pk_mul_f32 v[98:99], v[102:103], v[98:99]
	v_pk_fma_f32 v[110:111], v[120:121], v[122:123], v[120:121] op_sel_hi:[0,1,0]
	v_pk_fma_f32 v[112:113], v[120:121], v[124:125], v[120:121] op_sel_hi:[0,1,0]
	v_pk_mul_f32 v[122:123], v[104:105], v[118:119] op_sel_hi:[1,0]
	v_pk_mul_f32 v[118:119], v[102:103], v[118:119] op_sel_hi:[1,0]
	v_rcp_f32_e32 v112, v112
	v_rcp_f32_e32 v113, v113
	v_rcp_f32_e32 v110, v110
	v_rcp_f32_e32 v111, v111
	v_exp_f32_e32 v118, v118
	v_exp_f32_e32 v122, v122
	v_exp_f32_e32 v123, v123
	v_exp_f32_e32 v119, v119
	v_pk_mul_f32 v[108:109], v[108:109], v[110:111]
	v_pk_mul_f32 v[106:107], v[106:107], v[112:113]
	v_pk_fma_f32 v[110:111], v[120:121], v[122:123], v[120:121] op_sel_hi:[0,1,0]
	v_pk_fma_f32 v[112:113], v[120:121], v[118:119], v[120:121] op_sel_hi:[0,1,0]
	v_rcp_f32_e32 v112, v112
	v_rcp_f32_e32 v110, v110
	v_rcp_f32_e32 v111, v111
	v_rcp_f32_e32 v113, v113
	v_add_u32_e32 v104, 16, v145
	v_mad_i64_i32 v[104:105], s[44:45], v104, s29, v[114:115]
	v_pk_mul_f32 v[102:103], v[100:101], v[110:111]
	v_pk_mul_f32 v[100:101], v[98:99], v[112:113]
	v_cvt_pk_bf16_f32 v98, v106, v107
	v_cvt_pk_bf16_f32 v100, v100, v101
	v_cvt_pk_bf16_f32 v101, v102, v103
	ds_read2_b32 v[102:103], v146 offset0:32 offset1:48
	v_cvt_pk_bf16_f32 v99, v108, v109
	v_lshl_add_u64 v[104:105], v[104:105], 0, v[116:117]
	global_store_dwordx4 v[104:105], v[98:101], off
	v_pk_mul_f32 v[92:93], v[96:97], v[92:93]
	v_pk_mul_f32 v[90:91], v[94:95], v[90:91]
	s_waitcnt lgkmcnt(0)
	v_mul_f32_e32 v98, 0xbfb8aa3b, v102
	v_mul_f32_e32 v99, v102, v102
	v_pk_mul_f32 v[104:105], v[96:97], v[98:99] op_sel_hi:[1,0]
	v_pk_mul_f32 v[106:107], v[94:95], v[98:99] op_sel_hi:[1,0]
	v_rcp_f32_e32 v100, v99
	v_exp_f32_e32 v106, v106
	v_exp_f32_e32 v104, v104
	v_exp_f32_e32 v105, v105
	v_exp_f32_e32 v107, v107
	v_pk_mul_f32 v[84:85], v[88:89], v[84:85]
	v_pk_mul_f32 v[82:83], v[86:87], v[82:83]
	v_pk_fma_f32 v[94:95], v[100:101], v[104:105], v[100:101] op_sel_hi:[0,1,0]
	v_pk_fma_f32 v[96:97], v[100:101], v[106:107], v[100:101] op_sel_hi:[0,1,0]
	v_pk_mul_f32 v[104:105], v[88:89], v[98:99] op_sel_hi:[1,0]
	v_pk_mul_f32 v[98:99], v[86:87], v[98:99] op_sel_hi:[1,0]
	v_rcp_f32_e32 v96, v96
	v_rcp_f32_e32 v97, v97
	v_rcp_f32_e32 v94, v94
	v_rcp_f32_e32 v95, v95
	v_exp_f32_e32 v98, v98
	v_exp_f32_e32 v104, v104
	v_exp_f32_e32 v105, v105
	v_exp_f32_e32 v99, v99
	v_pk_mul_f32 v[92:93], v[92:93], v[94:95]
	v_pk_mul_f32 v[90:91], v[90:91], v[96:97]
	v_pk_fma_f32 v[94:95], v[100:101], v[104:105], v[100:101] op_sel_hi:[0,1,0]
	v_pk_fma_f32 v[96:97], v[100:101], v[98:99], v[100:101] op_sel_hi:[0,1,0]
	v_rcp_f32_e32 v96, v96
	v_rcp_f32_e32 v94, v94
	v_rcp_f32_e32 v95, v95
	v_rcp_f32_e32 v97, v97
	v_add_u32_e32 v88, 32, v145
	v_pk_mul_f32 v[74:75], v[78:79], v[74:75]
	v_pk_mul_f32 v[86:87], v[84:85], v[94:95]
	v_pk_mul_f32 v[84:85], v[82:83], v[96:97]
	v_cvt_pk_bf16_f32 v82, v90, v91
	v_cvt_pk_bf16_f32 v84, v84, v85
	v_cvt_pk_bf16_f32 v85, v86, v87
	v_mad_i64_i32 v[86:87], s[44:45], v88, s29, v[114:115]
	v_cvt_pk_bf16_f32 v83, v92, v93
;     __device__ __forceinline__ void operator()(const f32x4 (&acc)[2][2][4][2], const Unit& u, int wr, int wc, int fr, int fq) const {
;     ...
;             for (int m = 0; m < 4; ++m) {
;                 const int row = row0 + ai * HALF + m * 16;
;                 const float rs = rt.get(ai, m, fr), rsl = rs * -LOG2E_F, irs2 = __builtin_amdgcn_rcpf(rs * rs);
;                 float o[8];
; #pragma unroll
;                 for (int n = 0; n < 2; ++n) {
;                     const f32x4 a = acc[ai][0][m][n], b = acc[ai][1][m][n];
;                     const f32x4 t = a * rsl, ab = a * b;
;                     f32x4 e; e[0] = __builtin_amdgcn_exp2f(t[0]); e[1] = __builtin_amdgcn_exp2f(t[1]); e[2] = __builtin_amdgcn_exp2f(t[2]); e[3] = __builtin_amdgcn_exp2f(t[3]);
;                     const f32x4 d = e * irs2 + irs2;
;                     f32x4 r; r[0] = __builtin_amdgcn_rcpf(d[0]); r[1] = __builtin_amdgcn_rcpf(d[1]); r[2] = __builtin_amdgcn_rcpf(d[2]); r[3] = __builtin_amdgcn_rcpf(d[3]);
;                     const f32x4 q = ab * r;
;                     o[n * 4 + 0] = q[0]; o[n * 4 + 1] = q[1]; o[n * 4 + 2] = q[2]; o[n * 4 + 3] = q[3];
;                 }
;                 { const u32x4 pk_ = pack8(o); *(u32x4*)(O + (size_t)row * ldo + col0) = pk_;
	v_lshl_add_u64 v[86:87], v[86:87], 0, v[116:117]
	global_store_dwordx4 v[86:87], v[82:85], off
	v_pk_mul_f32 v[72:73], v[76:77], v[72:73]
	v_pk_mul_f32 v[66:67], v[70:71], v[66:67]
	v_mul_f32_e32 v82, 0xbfb8aa3b, v103
	v_mul_f32_e32 v83, v103, v103
	v_pk_mul_f32 v[86:87], v[78:79], v[82:83] op_sel_hi:[1,0]
	v_pk_mul_f32 v[88:89], v[76:77], v[82:83] op_sel_hi:[1,0]
	v_rcp_f32_e32 v84, v83
	v_exp_f32_e32 v88, v88
	v_exp_f32_e32 v86, v86
	v_exp_f32_e32 v87, v87
	v_exp_f32_e32 v89, v89
	v_pk_mul_f32 v[64:65], v[68:69], v[64:65]
	v_pk_mul_f32 v[58:59], v[62:63], v[58:59]
	v_pk_fma_f32 v[76:77], v[84:85], v[86:87], v[84:85] op_sel_hi:[0,1,0]
	v_pk_fma_f32 v[78:79], v[84:85], v[88:89], v[84:85] op_sel_hi:[0,1,0]
	v_pk_mul_f32 v[86:87], v[70:71], v[82:83] op_sel_hi:[1,0]
	v_pk_mul_f32 v[82:83], v[68:69], v[82:83] op_sel_hi:[1,0]
	v_rcp_f32_e32 v78, v78
	v_rcp_f32_e32 v79, v79
	v_rcp_f32_e32 v76, v76
	v_rcp_f32_e32 v77, v77
	v_exp_f32_e32 v82, v82
	v_exp_f32_e32 v86, v86
	v_exp_f32_e32 v87, v87
	v_exp_f32_e32 v83, v83
	v_pk_mul_f32 v[74:75], v[74:75], v[76:77]
	v_pk_mul_f32 v[72:73], v[72:73], v[78:79]
	v_pk_fma_f32 v[76:77], v[84:85], v[86:87], v[84:85] op_sel_hi:[0,1,0]
	v_pk_fma_f32 v[78:79], v[84:85], v[82:83], v[84:85] op_sel_hi:[0,1,0]
	v_rcp_f32_e32 v78, v78
	v_rcp_f32_e32 v76, v76
	v_rcp_f32_e32 v77, v77
	v_rcp_f32_e32 v79, v79
	v_add_u32_e32 v70, 48, v145
	v_mad_i64_i32 v[70:71], s[44:45], v70, s29, v[114:115]
	v_pk_mul_f32 v[68:69], v[66:67], v[76:77]
	v_pk_mul_f32 v[66:67], v[64:65], v[78:79]
	v_cvt_pk_bf16_f32 v64, v72, v73
	v_cvt_pk_bf16_f32 v66, v66, v67
	v_cvt_pk_bf16_f32 v67, v68, v69
	ds_read2_b32 v[68:69], v146 offset0:64 offset1:80
	v_cvt_pk_bf16_f32 v65, v74, v75
	v_lshl_add_u64 v[70:71], v[70:71], 0, v[116:117]
	global_store_dwordx4 v[70:71], v[64:67], off
	v_pk_mul_f32 v[56:57], v[60:61], v[56:57]
	v_pk_mul_f32 v[50:51], v[54:55], v[50:51]
	s_waitcnt lgkmcnt(0)
	v_mul_f32_e32 v64, 0xbfb8aa3b, v68
	v_mul_f32_e32 v65, v68, v68
	v_pk_mul_f32 v[70:71], v[62:63], v[64:65] op_sel_hi:[1,0]
	v_pk_mul_f32 v[72:73], v[60:61], v[64:65] op_sel_hi:[1,0]
	v_rcp_f32_e32 v66, v65
	v_exp_f32_e32 v72, v72
	v_exp_f32_e32 v70, v70
	v_exp_f32_e32 v71, v71
	v_exp_f32_e32 v73, v73
	v_add_u32_e32 v67, 0x80, v145
	v_pk_mul_f32 v[48:49], v[52:53], v[48:49]
	v_pk_fma_f32 v[60:61], v[66:67], v[70:71], v[66:67] op_sel_hi:[0,1,0]
	v_pk_fma_f32 v[62:63], v[66:67], v[72:73], v[66:67] op_sel_hi:[0,1,0]
	v_pk_mul_f32 v[70:71], v[54:55], v[64:65] op_sel_hi:[1,0]
	v_pk_mul_f32 v[64:65], v[52:53], v[64:65] op_sel_hi:[1,0]
	v_rcp_f32_e32 v62, v62
	v_rcp_f32_e32 v63, v63
	v_rcp_f32_e32 v60, v60
	v_rcp_f32_e32 v61, v61
	v_exp_f32_e32 v64, v64
	v_exp_f32_e32 v70, v70
	v_exp_f32_e32 v71, v71
	v_exp_f32_e32 v65, v65
	v_pk_mul_f32 v[58:59], v[58:59], v[60:61]
	v_pk_mul_f32 v[56:57], v[56:57], v[62:63]
	v_pk_fma_f32 v[60:61], v[66:67], v[70:71], v[66:67] op_sel_hi:[0,1,0]
	v_pk_fma_f32 v[62:63], v[66:67], v[64:65], v[66:67] op_sel_hi:[0,1,0]
	v_rcp_f32_e32 v62, v62
	v_rcp_f32_e32 v60, v60
	v_rcp_f32_e32 v61, v61
	v_rcp_f32_e32 v63, v63
	v_pk_mul_f32 v[42:43], v[46:47], v[42:43]
	v_pk_mul_f32 v[40:41], v[44:45], v[40:41]
	v_pk_mul_f32 v[52:53], v[50:51], v[60:61]
	v_pk_mul_f32 v[50:51], v[48:49], v[62:63]
	v_cvt_pk_bf16_f32 v48, v56, v57
	v_cvt_pk_bf16_f32 v50, v50, v51
	v_cvt_pk_bf16_f32 v51, v52, v53
	v_mad_i64_i32 v[52:53], s[44:45], v67, s29, v[114:115]
	v_cvt_pk_bf16_f32 v49, v58, v59
	v_lshl_add_u64 v[52:53], v[52:53], 0, v[116:117]
	global_store_dwordx4 v[52:53], v[48:51], off
	v_pk_mul_f32 v[34:35], v[38:39], v[34:35]
	v_pk_mul_f32 v[32:33], v[36:37], v[32:33]
	v_mul_f32_e32 v48, 0xbfb8aa3b, v69
	v_mul_f32_e32 v49, v69, v69
	v_pk_mul_f32 v[52:53], v[46:47], v[48:49] op_sel_hi:[1,0]
	v_pk_mul_f32 v[54:55], v[44:45], v[48:49] op_sel_hi:[1,0]
	v_rcp_f32_e32 v50, v49
	v_exp_f32_e32 v54, v54
	v_exp_f32_e32 v52, v52
	v_exp_f32_e32 v53, v53
	v_exp_f32_e32 v55, v55
	v_pk_mul_f32 v[26:27], v[30:31], v[26:27]
	v_pk_mul_f32 v[24:25], v[28:29], v[24:25]
	v_pk_fma_f32 v[44:45], v[50:51], v[52:53], v[50:51] op_sel_hi:[0,1,0]
	v_pk_fma_f32 v[46:47], v[50:51], v[54:55], v[50:51] op_sel_hi:[0,1,0]
	v_pk_mul_f32 v[52:53], v[38:39], v[48:49] op_sel_hi:[1,0]
	v_pk_mul_f32 v[48:49], v[36:37], v[48:49] op_sel_hi:[1,0]
	v_rcp_f32_e32 v46, v46
	v_rcp_f32_e32 v47, v47
	v_rcp_f32_e32 v44, v44
	v_rcp_f32_e32 v45, v45
	v_exp_f32_e32 v48, v48
	v_exp_f32_e32 v52, v52
	v_exp_f32_e32 v53, v53
	v_exp_f32_e32 v49, v49
	v_pk_mul_f32 v[42:43], v[42:43], v[44:45]
	v_pk_mul_f32 v[40:41], v[40:41], v[46:47]
	v_pk_fma_f32 v[44:45], v[50:51], v[52:53], v[50:51] op_sel_hi:[0,1,0]
	v_pk_fma_f32 v[46:47], v[50:51], v[48:49], v[50:51] op_sel_hi:[0,1,0]
	v_rcp_f32_e32 v46, v46
	v_rcp_f32_e32 v44, v44
	v_rcp_f32_e32 v45, v45
	v_rcp_f32_e32 v47, v47
	v_add_u32_e32 v38, 0x90, v145
	v_mad_i64_i32 v[38:39], s[44:45], v38, s29, v[114:115]
	v_pk_mul_f32 v[36:37], v[34:35], v[44:45]
	v_pk_mul_f32 v[34:35], v[32:33], v[46:47]
	v_cvt_pk_bf16_f32 v32, v40, v41
	v_cvt_pk_bf16_f32 v34, v34, v35
	v_cvt_pk_bf16_f32 v35, v36, v37
	ds_read2_b32 v[36:37], v146 offset0:96 offset1:112
	v_cvt_pk_bf16_f32 v33, v42, v43
	v_lshl_add_u64 v[38:39], v[38:39], 0, v[116:117]
	global_store_dwordx4 v[38:39], v[32:35], off
	v_pk_mul_f32 v[18:19], v[22:23], v[18:19]
	v_pk_mul_f32 v[16:17], v[20:21], v[16:17]
	s_waitcnt lgkmcnt(0)
; #define PG8_BAR __builtin_amdgcn_s_barrier()
; template <class Epi, class Sched, bool ALIGN_EPI = false, bool SP2 = false>
; __device__ __forceinline__ void gemm_phase(PG8_LAS unsigned char* lds, const Gemm g, const Sched& S, const Epi& E) {
;     ...
;         if constexpr (ALIGN_EPI) { if (wr == 1) PG8_BAR; }
;     __device__ __forceinline__ void operator()(const f32x4 (&acc)[2][2][4][2], const Unit& u, int wr, int wc, int fr, int fq) const {
;     ...
;             for (int m = 0; m < 4; ++m) {
;                 const int row = row0 + ai * HALF + m * 16;
;                 const float rs = rt.get(ai, m, fr), rsl = rs * -LOG2E_F, irs2 = __builtin_amdgcn_rcpf(rs * rs);
;                 float o[8];
; #pragma unroll
;                 for (int n = 0; n < 2; ++n) {
;                     const f32x4 a = acc[ai][0][m][n], b = acc[ai][1][m][n];
;                     const f32x4 t = a * rsl, ab = a * b;
;                     f32x4 e; e[0] = __builtin_amdgcn_exp2f(t[0]); e[1] = __builtin_amdgcn_exp2f(t[1]); e[2] = __builtin_amdgcn_exp2f(t[2]); e[3] = __builtin_amdgcn_exp2f(t[3]);
;                     const f32x4 d = e * irs2 + irs2;
;                     f32x4 r; r[0] = __builtin_amdgcn_rcpf(d[0]); r[1] = __builtin_amdgcn_rcpf(d[1]); r[2] = __builtin_amdgcn_rcpf(d[2]); r[3] = __builtin_amdgcn_rcpf(d[3]);
;                     const f32x4 q = ab * r;
;                     o[n * 4 + 0] = q[0]; o[n * 4 + 1] = q[1]; o[n * 4 + 2] = q[2]; o[n * 4 + 3] = q[3];
;                 }
;                 { const u32x4 pk_ = pack8(o); *(u32x4*)(O + (size_t)row * ldo + col0) = pk_;
;     ...
;                   *(volatile u32x4*)(O + (size_t)row * ldo + col0) = pk_;
;     ...
;                 }
	v_mul_f32_e32 v32, 0xbfb8aa3b, v36
	v_mul_f32_e32 v33, v36, v36
	v_pk_mul_f32 v[38:39], v[30:31], v[32:33] op_sel_hi:[1,0]
	v_pk_mul_f32 v[40:41], v[28:29], v[32:33] op_sel_hi:[1,0]
	v_rcp_f32_e32 v34, v33
	v_exp_f32_e32 v40, v40
	v_exp_f32_e32 v38, v38
	v_exp_f32_e32 v39, v39
	v_exp_f32_e32 v41, v41
	v_pk_mul_f32 v[10:11], v[14:15], v[10:11]
	v_pk_mul_f32 v[8:9], v[12:13], v[8:9]
	v_pk_fma_f32 v[28:29], v[34:35], v[38:39], v[34:35] op_sel_hi:[0,1,0]
	v_pk_fma_f32 v[30:31], v[34:35], v[40:41], v[34:35] op_sel_hi:[0,1,0]
	v_pk_mul_f32 v[38:39], v[22:23], v[32:33] op_sel_hi:[1,0]
	v_pk_mul_f32 v[32:33], v[20:21], v[32:33] op_sel_hi:[1,0]
	v_rcp_f32_e32 v30, v30
	v_rcp_f32_e32 v31, v31
	v_rcp_f32_e32 v28, v28
	v_rcp_f32_e32 v29, v29
	v_exp_f32_e32 v32, v32
	v_exp_f32_e32 v38, v38
	v_exp_f32_e32 v39, v39
	v_exp_f32_e32 v33, v33
	v_pk_mul_f32 v[26:27], v[26:27], v[28:29]
	v_pk_mul_f32 v[24:25], v[24:25], v[30:31]
	v_pk_fma_f32 v[28:29], v[34:35], v[38:39], v[34:35] op_sel_hi:[0,1,0]
	v_pk_fma_f32 v[30:31], v[34:35], v[32:33], v[34:35] op_sel_hi:[0,1,0]
	v_rcp_f32_e32 v30, v30
	v_rcp_f32_e32 v28, v28
	v_rcp_f32_e32 v29, v29
	v_rcp_f32_e32 v31, v31
	v_add_u32_e32 v22, 0xa0, v145
	v_pk_mul_f32 v[2:3], v[6:7], v[2:3]
	v_pk_mul_f32 v[20:21], v[18:19], v[28:29]
	v_pk_mul_f32 v[18:19], v[16:17], v[30:31]
	v_cvt_pk_bf16_f32 v16, v24, v25
	v_cvt_pk_bf16_f32 v18, v18, v19
	v_cvt_pk_bf16_f32 v19, v20, v21
	v_mad_i64_i32 v[20:21], s[44:45], v22, s29, v[114:115]
	v_cvt_pk_bf16_f32 v17, v26, v27
	v_lshl_add_u64 v[20:21], v[20:21], 0, v[116:117]
	global_store_dwordx4 v[20:21], v[16:19], off
	v_pk_mul_f32 v[0:1], v[4:5], v[0:1]
	s_andn2_b64 vcc, exec, s[4:5]
	v_mul_f32_e32 v16, 0xbfb8aa3b, v37
	v_mul_f32_e32 v17, v37, v37
	v_pk_mul_f32 v[20:21], v[14:15], v[16:17] op_sel_hi:[1,0]
	v_pk_mul_f32 v[22:23], v[12:13], v[16:17] op_sel_hi:[1,0]
	v_rcp_f32_e32 v18, v17
	v_exp_f32_e32 v22, v22
	v_exp_f32_e32 v20, v20
	v_exp_f32_e32 v21, v21
	v_exp_f32_e32 v23, v23
	s_mov_b64 s[4:5], -1
	v_pk_fma_f32 v[12:13], v[18:19], v[20:21], v[18:19] op_sel_hi:[0,1,0]
	v_pk_fma_f32 v[14:15], v[18:19], v[22:23], v[18:19] op_sel_hi:[0,1,0]
	v_pk_mul_f32 v[20:21], v[6:7], v[16:17] op_sel_hi:[1,0]
	v_pk_mul_f32 v[16:17], v[4:5], v[16:17] op_sel_hi:[1,0]
	v_rcp_f32_e32 v14, v14
	v_rcp_f32_e32 v15, v15
	v_rcp_f32_e32 v12, v12
	v_rcp_f32_e32 v13, v13
	v_exp_f32_e32 v16, v16
	v_exp_f32_e32 v20, v20
	v_exp_f32_e32 v21, v21
	v_exp_f32_e32 v17, v17
	v_pk_mul_f32 v[10:11], v[10:11], v[12:13]
	v_pk_mul_f32 v[8:9], v[8:9], v[14:15]
	v_pk_fma_f32 v[12:13], v[18:19], v[20:21], v[18:19] op_sel_hi:[0,1,0]
	v_pk_fma_f32 v[14:15], v[18:19], v[16:17], v[18:19] op_sel_hi:[0,1,0]
	v_rcp_f32_e32 v14, v14
	v_rcp_f32_e32 v12, v12
	v_rcp_f32_e32 v13, v13
	v_rcp_f32_e32 v15, v15
	v_add_u32_e32 v6, 0xb0, v145
	v_pk_mul_f32 v[4:5], v[2:3], v[12:13]
	v_pk_mul_f32 v[2:3], v[0:1], v[14:15]
	v_cvt_pk_bf16_f32 v0, v8, v9
	v_cvt_pk_bf16_f32 v2, v2, v3
	v_cvt_pk_bf16_f32 v3, v4, v5
	v_mad_i64_i32 v[4:5], s[44:45], v6, s29, v[114:115]
	v_cvt_pk_bf16_f32 v1, v10, v11
	v_lshl_add_u64 v[4:5], v[4:5], 0, v[116:117]
	global_store_dwordx4 v[4:5], v[0:3], off
	s_cbranch_vccnz .LBB0_106
	s_branch .LBB0_105
